# phase 0 conversion tasks de-serialised: M1 fold (64 strided loads, was one wait per load), w_in transpose / plain copy and w_out transpose (64 row loads in flight instead of 4 batches of 16 or 32 pair
# speedup vs baseline: 1.0346x; 1.0163x over previous
.LBB0_802:
	s_or_b64 exec, exec, s[28:29]
	s_lshl_b32 s1, s8, 10
	v_readlane_b32 s40, v252, 1
	s_and_b32 s0, s1, 0x40000
	v_readlane_b32 s44, v252, 5
	v_readlane_b32 s45, v252, 6
	s_add_u32 s9, s44, s0
	s_addc_u32 s11, s45, 0
	s_and_b32 s1, s1, 0x30000
	s_add_u32 s10, s9, s1
	v_mov_b32_e32 v10, v151
	s_waitcnt lgkmcnt(0)
	s_barrier
	s_addc_u32 s11, s11, 0
	s_movk_i32 s1, 0x1000
	v_ashrrev_i32_e32 v11, 31, v10
	v_lshl_add_u64 v[6:7], v[10:11], 2, s[10:11]
	s_waitcnt vmcnt(0)
	s_and_b32 s8, s8, 0xff
	v_readlane_b32 s41, v252, 2
	v_readlane_b32 s42, v252, 3
	v_readlane_b32 s43, v252, 4
	v_readlane_b32 s46, v252, 7
	v_readlane_b32 s47, v252, 8
	v_readlane_b32 s1, v253, 8
	s_add_u32 s0, s1, s0
	v_readlane_b32 s1, v253, 9
	s_addc_u32 s1, s1, 0
	s_lshl_b32 s50, s8, 1
	v_mov_b32_e32 v8, v6
	v_mov_b32_e32 v9, v7
	global_load_dword v32, v[8:9], off
	global_load_dword v33, v[8:9], off offset:1024
	global_load_dword v34, v[8:9], off offset:2048
	global_load_dword v35, v[8:9], off offset:3072
	v_add_co_u32_e32 v8, vcc, 0x1000, v8
	s_nop 0
	v_addc_co_u32_e32 v9, vcc, 0, v9, vcc
	global_load_dword v36, v[8:9], off
	global_load_dword v37, v[8:9], off offset:1024
	global_load_dword v38, v[8:9], off offset:2048
	global_load_dword v39, v[8:9], off offset:3072
	v_add_co_u32_e32 v8, vcc, 0x1000, v8
	s_nop 0
	v_addc_co_u32_e32 v9, vcc, 0, v9, vcc
	global_load_dword v40, v[8:9], off
	global_load_dword v41, v[8:9], off offset:1024
	global_load_dword v42, v[8:9], off offset:2048
	global_load_dword v43, v[8:9], off offset:3072
	v_add_co_u32_e32 v8, vcc, 0x1000, v8
	s_nop 0
	v_addc_co_u32_e32 v9, vcc, 0, v9, vcc
	global_load_dword v44, v[8:9], off
	global_load_dword v45, v[8:9], off offset:1024
	global_load_dword v46, v[8:9], off offset:2048
	global_load_dword v47, v[8:9], off offset:3072
	v_add_co_u32_e32 v8, vcc, 0x1000, v8
	s_nop 0
	v_addc_co_u32_e32 v9, vcc, 0, v9, vcc
	global_load_dword v48, v[8:9], off
	global_load_dword v49, v[8:9], off offset:1024
	global_load_dword v50, v[8:9], off offset:2048
	global_load_dword v51, v[8:9], off offset:3072
	v_add_co_u32_e32 v8, vcc, 0x1000, v8
	s_nop 0
	v_addc_co_u32_e32 v9, vcc, 0, v9, vcc
	global_load_dword v52, v[8:9], off
	global_load_dword v53, v[8:9], off offset:1024
	global_load_dword v54, v[8:9], off offset:2048
	global_load_dword v55, v[8:9], off offset:3072
	v_add_co_u32_e32 v8, vcc, 0x1000, v8
	s_nop 0
	v_addc_co_u32_e32 v9, vcc, 0, v9, vcc
	global_load_dword v56, v[8:9], off
	global_load_dword v57, v[8:9], off offset:1024
	global_load_dword v58, v[8:9], off offset:2048
	global_load_dword v59, v[8:9], off offset:3072
	v_add_co_u32_e32 v8, vcc, 0x1000, v8
	s_nop 0
	v_addc_co_u32_e32 v9, vcc, 0, v9, vcc
	global_load_dword v60, v[8:9], off
	global_load_dword v61, v[8:9], off offset:1024
	global_load_dword v62, v[8:9], off offset:2048
	global_load_dword v63, v[8:9], off offset:3072
	v_add_co_u32_e32 v8, vcc, 0x1000, v8
	s_nop 0
	v_addc_co_u32_e32 v9, vcc, 0, v9, vcc
	global_load_dword v64, v[8:9], off
	global_load_dword v65, v[8:9], off offset:1024
	global_load_dword v66, v[8:9], off offset:2048
	global_load_dword v67, v[8:9], off offset:3072
	v_add_co_u32_e32 v8, vcc, 0x1000, v8
	s_nop 0
	v_addc_co_u32_e32 v9, vcc, 0, v9, vcc
	global_load_dword v68, v[8:9], off
	global_load_dword v69, v[8:9], off offset:1024
	global_load_dword v70, v[8:9], off offset:2048
	global_load_dword v71, v[8:9], off offset:3072
	v_add_co_u32_e32 v8, vcc, 0x1000, v8
	s_nop 0
	v_addc_co_u32_e32 v9, vcc, 0, v9, vcc
	global_load_dword v72, v[8:9], off
	global_load_dword v73, v[8:9], off offset:1024
	global_load_dword v74, v[8:9], off offset:2048
	global_load_dword v75, v[8:9], off offset:3072
	v_add_co_u32_e32 v8, vcc, 0x1000, v8
	s_nop 0
	v_addc_co_u32_e32 v9, vcc, 0, v9, vcc
	global_load_dword v76, v[8:9], off
	global_load_dword v77, v[8:9], off offset:1024
	global_load_dword v78, v[8:9], off offset:2048
	global_load_dword v79, v[8:9], off offset:3072
	v_add_co_u32_e32 v8, vcc, 0x1000, v8
	s_nop 0
	v_addc_co_u32_e32 v9, vcc, 0, v9, vcc
	global_load_dword v80, v[8:9], off
	global_load_dword v81, v[8:9], off offset:1024
	global_load_dword v82, v[8:9], off offset:2048
	global_load_dword v83, v[8:9], off offset:3072
	v_add_co_u32_e32 v8, vcc, 0x1000, v8
	s_nop 0
	v_addc_co_u32_e32 v9, vcc, 0, v9, vcc
	global_load_dword v84, v[8:9], off
	global_load_dword v85, v[8:9], off offset:1024
	global_load_dword v86, v[8:9], off offset:2048
	global_load_dword v87, v[8:9], off offset:3072
	v_add_co_u32_e32 v8, vcc, 0x1000, v8
	s_nop 0
	v_addc_co_u32_e32 v9, vcc, 0, v9, vcc
	global_load_dword v88, v[8:9], off
	global_load_dword v89, v[8:9], off offset:1024
	global_load_dword v90, v[8:9], off offset:2048
	global_load_dword v91, v[8:9], off offset:3072
	v_add_co_u32_e32 v8, vcc, 0x1000, v8
	s_nop 0
	v_addc_co_u32_e32 v9, vcc, 0, v9, vcc
	ds_read_b128 v[96:99], v1 offset:0
	ds_read_b128 v[100:103], v1 offset:256
	ds_read_b128 v[104:107], v1 offset:16
	ds_read_b128 v[108:111], v1 offset:272
	s_waitcnt vmcnt(56) lgkmcnt(2)
	v_fma_f32 v12, v32, v96, 0
	v_fma_f32 v0, v32, v100, 0
	v_fmac_f32_e32 v12, v33, v97
	v_fmac_f32_e32 v0, v33, v101
	v_fmac_f32_e32 v12, v34, v98
	v_fmac_f32_e32 v0, v34, v102
	v_fmac_f32_e32 v12, v35, v99
	v_fmac_f32_e32 v0, v35, v103
	global_load_dword v92, v[8:9], off
	global_load_dword v93, v[8:9], off offset:1024
	global_load_dword v94, v[8:9], off offset:2048
	global_load_dword v95, v[8:9], off offset:3072
	v_add_co_u32_e32 v8, vcc, 0x1000, v8
	s_nop 0
	v_addc_co_u32_e32 v9, vcc, 0, v9, vcc
	ds_read_b128 v[96:99], v1 offset:32
	ds_read_b128 v[100:103], v1 offset:288
	s_waitcnt vmcnt(56) lgkmcnt(2)
	v_fmac_f32_e32 v12, v36, v104
	v_fmac_f32_e32 v0, v36, v108
	v_fmac_f32_e32 v12, v37, v105
	v_fmac_f32_e32 v0, v37, v109
	v_fmac_f32_e32 v12, v38, v106
	v_fmac_f32_e32 v0, v38, v110
	v_fmac_f32_e32 v12, v39, v107
	v_fmac_f32_e32 v0, v39, v111
	ds_read_b128 v[104:107], v1 offset:48
	ds_read_b128 v[108:111], v1 offset:304
	s_waitcnt vmcnt(52) lgkmcnt(2)
	v_fmac_f32_e32 v12, v40, v96
	v_fmac_f32_e32 v0, v40, v100
	v_fmac_f32_e32 v12, v41, v97
	v_fmac_f32_e32 v0, v41, v101
	v_fmac_f32_e32 v12, v42, v98
	v_fmac_f32_e32 v0, v42, v102
	v_fmac_f32_e32 v12, v43, v99
	v_fmac_f32_e32 v0, v43, v103
	ds_read_b128 v[96:99], v1 offset:64
	ds_read_b128 v[100:103], v1 offset:320
	s_waitcnt vmcnt(48) lgkmcnt(2)
	v_fmac_f32_e32 v12, v44, v104
	v_fmac_f32_e32 v0, v44, v108
	v_fmac_f32_e32 v12, v45, v105
	v_fmac_f32_e32 v0, v45, v109
	v_fmac_f32_e32 v12, v46, v106
	v_fmac_f32_e32 v0, v46, v110
	v_fmac_f32_e32 v12, v47, v107
	v_fmac_f32_e32 v0, v47, v111
	ds_read_b128 v[104:107], v1 offset:80
	ds_read_b128 v[108:111], v1 offset:336
	s_waitcnt vmcnt(44) lgkmcnt(2)
	v_fmac_f32_e32 v12, v48, v96
	v_fmac_f32_e32 v0, v48, v100
	v_fmac_f32_e32 v12, v49, v97
	v_fmac_f32_e32 v0, v49, v101
	v_fmac_f32_e32 v12, v50, v98
	v_fmac_f32_e32 v0, v50, v102
	v_fmac_f32_e32 v12, v51, v99
	v_fmac_f32_e32 v0, v51, v103
	ds_read_b128 v[96:99], v1 offset:96
	ds_read_b128 v[100:103], v1 offset:352
	s_waitcnt vmcnt(40) lgkmcnt(2)
	v_fmac_f32_e32 v12, v52, v104
	v_fmac_f32_e32 v0, v52, v108
	v_fmac_f32_e32 v12, v53, v105
	v_fmac_f32_e32 v0, v53, v109
	v_fmac_f32_e32 v12, v54, v106
	v_fmac_f32_e32 v0, v54, v110
	v_fmac_f32_e32 v12, v55, v107
	v_fmac_f32_e32 v0, v55, v111
	ds_read_b128 v[104:107], v1 offset:112
	ds_read_b128 v[108:111], v1 offset:368
	s_waitcnt vmcnt(36) lgkmcnt(2)
	v_fmac_f32_e32 v12, v56, v96
	v_fmac_f32_e32 v0, v56, v100
	v_fmac_f32_e32 v12, v57, v97
	v_fmac_f32_e32 v0, v57, v101
	v_fmac_f32_e32 v12, v58, v98
	v_fmac_f32_e32 v0, v58, v102
	v_fmac_f32_e32 v12, v59, v99
	v_fmac_f32_e32 v0, v59, v103
	ds_read_b128 v[96:99], v1 offset:128
	ds_read_b128 v[100:103], v1 offset:384
	s_waitcnt vmcnt(32) lgkmcnt(2)
	v_fmac_f32_e32 v12, v60, v104
	v_fmac_f32_e32 v0, v60, v108
	v_fmac_f32_e32 v12, v61, v105
	v_fmac_f32_e32 v0, v61, v109
	v_fmac_f32_e32 v12, v62, v106
	v_fmac_f32_e32 v0, v62, v110
	v_fmac_f32_e32 v12, v63, v107
	v_fmac_f32_e32 v0, v63, v111
	ds_read_b128 v[104:107], v1 offset:144
	ds_read_b128 v[108:111], v1 offset:400
	s_waitcnt vmcnt(28) lgkmcnt(2)
	v_fmac_f32_e32 v12, v64, v96
	v_fmac_f32_e32 v0, v64, v100
	v_fmac_f32_e32 v12, v65, v97
	v_fmac_f32_e32 v0, v65, v101
	v_fmac_f32_e32 v12, v66, v98
	v_fmac_f32_e32 v0, v66, v102
	v_fmac_f32_e32 v12, v67, v99
	v_fmac_f32_e32 v0, v67, v103
	ds_read_b128 v[96:99], v1 offset:160
	ds_read_b128 v[100:103], v1 offset:416
	s_waitcnt vmcnt(24) lgkmcnt(2)
	v_fmac_f32_e32 v12, v68, v104
	v_fmac_f32_e32 v0, v68, v108
	v_fmac_f32_e32 v12, v69, v105
	v_fmac_f32_e32 v0, v69, v109
	v_fmac_f32_e32 v12, v70, v106
	v_fmac_f32_e32 v0, v70, v110
	v_fmac_f32_e32 v12, v71, v107
	v_fmac_f32_e32 v0, v71, v111
	ds_read_b128 v[104:107], v1 offset:176
	ds_read_b128 v[108:111], v1 offset:432
	s_waitcnt vmcnt(20) lgkmcnt(2)
	v_fmac_f32_e32 v12, v72, v96
	v_fmac_f32_e32 v0, v72, v100
	v_fmac_f32_e32 v12, v73, v97
	v_fmac_f32_e32 v0, v73, v101
	v_fmac_f32_e32 v12, v74, v98
	v_fmac_f32_e32 v0, v74, v102
	v_fmac_f32_e32 v12, v75, v99
	v_fmac_f32_e32 v0, v75, v103
	ds_read_b128 v[96:99], v1 offset:192
	ds_read_b128 v[100:103], v1 offset:448
	s_waitcnt vmcnt(16) lgkmcnt(2)
	v_fmac_f32_e32 v12, v76, v104
	v_fmac_f32_e32 v0, v76, v108
	v_fmac_f32_e32 v12, v77, v105
	v_fmac_f32_e32 v0, v77, v109
	v_fmac_f32_e32 v12, v78, v106
	v_fmac_f32_e32 v0, v78, v110
	v_fmac_f32_e32 v12, v79, v107
	v_fmac_f32_e32 v0, v79, v111
	ds_read_b128 v[104:107], v1 offset:208
	ds_read_b128 v[108:111], v1 offset:464
	s_waitcnt vmcnt(12) lgkmcnt(2)
	v_fmac_f32_e32 v12, v80, v96
	v_fmac_f32_e32 v0, v80, v100
	v_fmac_f32_e32 v12, v81, v97
	v_fmac_f32_e32 v0, v81, v101
	v_fmac_f32_e32 v12, v82, v98
	v_fmac_f32_e32 v0, v82, v102
	v_fmac_f32_e32 v12, v83, v99
	v_fmac_f32_e32 v0, v83, v103
	ds_read_b128 v[96:99], v1 offset:224
	ds_read_b128 v[100:103], v1 offset:480
	s_waitcnt vmcnt(8) lgkmcnt(2)
	v_fmac_f32_e32 v12, v84, v104
	v_fmac_f32_e32 v0, v84, v108
	v_fmac_f32_e32 v12, v85, v105
	v_fmac_f32_e32 v0, v85, v109
	v_fmac_f32_e32 v12, v86, v106
	v_fmac_f32_e32 v0, v86, v110
	v_fmac_f32_e32 v12, v87, v107
	v_fmac_f32_e32 v0, v87, v111
	ds_read_b128 v[104:107], v1 offset:240
	ds_read_b128 v[108:111], v1 offset:496
	s_waitcnt vmcnt(4) lgkmcnt(2)
	v_fmac_f32_e32 v12, v88, v96
	v_fmac_f32_e32 v0, v88, v100
	v_fmac_f32_e32 v12, v89, v97
	v_fmac_f32_e32 v0, v89, v101
	v_fmac_f32_e32 v12, v90, v98
	v_fmac_f32_e32 v0, v90, v102
	v_fmac_f32_e32 v12, v91, v99
	v_fmac_f32_e32 v0, v91, v103
	s_waitcnt vmcnt(0) lgkmcnt(0)
	v_fmac_f32_e32 v12, v92, v104
	v_fmac_f32_e32 v0, v92, v108
	v_fmac_f32_e32 v12, v93, v105
	v_fmac_f32_e32 v0, v93, v109
	v_fmac_f32_e32 v12, v94, v106
	v_fmac_f32_e32 v0, v94, v110
	v_fmac_f32_e32 v12, v95, v107
	v_fmac_f32_e32 v0, v95, v111
	v_lshlrev_b64 v[2:3], 9, v[10:11]
	v_lshl_add_u64 v[2:3], s[0:1], 0, v[2:3]
	v_cvt_pk_bf16_f32 v4, v12, s0
	v_lshl_add_u64 v[2:3], v[2:3], 0, s[50:51]
	global_store_short v[2:3], v4, off
	v_add_co_u32_e32 v2, vcc, 0x20000, v2
	v_cvt_pk_bf16_f32 v0, v0, s0
	s_nop 0
	v_addc_co_u32_e32 v3, vcc, 0, v3, vcc
	s_movk_i32 s50, 0x3000
	global_store_short v[2:3], v0, off
	s_mov_b64 s[0:1], 0

.LBB0_804:
	s_add_i32 s0, s7, 0xfffffc90
	s_bfe_u32 s1, s0, 0x40002
	s_lshl_b32 s0, s0, 14
	s_and_b32 s0, s0, 0x100000
	v_readlane_b32 s52, v252, 29
	s_and_b32 s10, s7, 3
	s_lshl_b32 s8, s0, 2
	v_readlane_b32 s62, v252, 39
	v_readlane_b32 s63, v252, 40
	s_add_u32 s8, s62, s8
	s_addc_u32 s9, s63, 0
	s_lshl_b32 s11, s1, 18
	s_add_u32 s8, s8, s11
	s_addc_u32 s9, s9, 0
	s_lshl_b32 s11, s10, 10
	s_add_u32 s8, s8, s11
	v_mov_b32_e32 v2, v151
	s_addc_u32 s9, s9, 0
	s_waitcnt vmcnt(63) expcnt(7) lgkmcnt(15)
	v_ashrrev_i32_e32 v3, 31, v2
	v_lshl_add_u64 v[4:5], v[2:3], 2, s[8:9]
	s_movk_i32 s8, 0x2000
	v_add_co_u32_e32 v6, vcc, s8, v4
	s_movk_i32 s8, 0x4000
	s_nop 0
	v_addc_co_u32_e32 v7, vcc, 0, v5, vcc
	s_barrier
	s_movk_i32 s9, 0x90
	v_mul_lo_u32 v0, v2, s9
	s_lshl_b32 s0, s0, 1
	v_readlane_b32 s11, v253, 28
	s_add_u32 s0, s11, s0
	v_readlane_b32 s11, v253, 29
	s_addc_u32 s11, s11, 0
	s_lshl_b32 s10, s10, 19
	s_add_u32 s0, s0, s10
	s_addc_u32 s10, s11, 0
	s_lshl_b32 s1, s1, 7
	s_add_u32 s0, s0, s1
	s_addc_u32 s1, s10, 0
	v_readlane_b32 s53, v252, 30
	v_readlane_b32 s54, v252, 31
	v_readlane_b32 s55, v252, 32
	v_readlane_b32 s56, v252, 33
	v_readlane_b32 s57, v252, 34
	v_readlane_b32 s58, v252, 35
	v_readlane_b32 s59, v252, 36
	v_readlane_b32 s60, v252, 37
	v_readlane_b32 s61, v252, 38
	v_readlane_b32 s64, v252, 41
	v_readlane_b32 s65, v252, 42
	v_readlane_b32 s66, v252, 43
	v_readlane_b32 s67, v252, 44
	v_mov_b32_e32 v24, v4
	v_mov_b32_e32 v25, v5
	global_load_dword v32, v[24:25], off
	v_add_co_u32_e32 v24, vcc, 0x1000, v24
	s_nop 0
	v_addc_co_u32_e32 v25, vcc, 0, v25, vcc
	global_load_dword v33, v[24:25], off
	v_add_co_u32_e32 v24, vcc, 0x1000, v24
	s_nop 0
	v_addc_co_u32_e32 v25, vcc, 0, v25, vcc
	global_load_dword v34, v[24:25], off
	v_add_co_u32_e32 v24, vcc, 0x1000, v24
	s_nop 0
	v_addc_co_u32_e32 v25, vcc, 0, v25, vcc
	global_load_dword v35, v[24:25], off
	v_add_co_u32_e32 v24, vcc, 0x1000, v24
	s_nop 0
	v_addc_co_u32_e32 v25, vcc, 0, v25, vcc
	global_load_dword v36, v[24:25], off
	v_add_co_u32_e32 v24, vcc, 0x1000, v24
	s_nop 0
	v_addc_co_u32_e32 v25, vcc, 0, v25, vcc
	global_load_dword v37, v[24:25], off
	v_add_co_u32_e32 v24, vcc, 0x1000, v24
	s_nop 0
	v_addc_co_u32_e32 v25, vcc, 0, v25, vcc
	global_load_dword v38, v[24:25], off
	v_add_co_u32_e32 v24, vcc, 0x1000, v24
	s_nop 0
	v_addc_co_u32_e32 v25, vcc, 0, v25, vcc
	global_load_dword v39, v[24:25], off
	v_add_co_u32_e32 v24, vcc, 0x1000, v24
	s_nop 0
	v_addc_co_u32_e32 v25, vcc, 0, v25, vcc
	global_load_dword v40, v[24:25], off
	v_add_co_u32_e32 v24, vcc, 0x1000, v24
	s_nop 0
	v_addc_co_u32_e32 v25, vcc, 0, v25, vcc
	global_load_dword v41, v[24:25], off
	v_add_co_u32_e32 v24, vcc, 0x1000, v24
	s_nop 0
	v_addc_co_u32_e32 v25, vcc, 0, v25, vcc
	global_load_dword v42, v[24:25], off
	v_add_co_u32_e32 v24, vcc, 0x1000, v24
	s_nop 0
	v_addc_co_u32_e32 v25, vcc, 0, v25, vcc
	global_load_dword v43, v[24:25], off
	v_add_co_u32_e32 v24, vcc, 0x1000, v24
	s_nop 0
	v_addc_co_u32_e32 v25, vcc, 0, v25, vcc
	global_load_dword v44, v[24:25], off
	v_add_co_u32_e32 v24, vcc, 0x1000, v24
	s_nop 0
	v_addc_co_u32_e32 v25, vcc, 0, v25, vcc
	global_load_dword v45, v[24:25], off
	v_add_co_u32_e32 v24, vcc, 0x1000, v24
	s_nop 0
	v_addc_co_u32_e32 v25, vcc, 0, v25, vcc
	global_load_dword v46, v[24:25], off
	v_add_co_u32_e32 v24, vcc, 0x1000, v24
	s_nop 0
	v_addc_co_u32_e32 v25, vcc, 0, v25, vcc
	global_load_dword v47, v[24:25], off
	v_add_co_u32_e32 v24, vcc, 0x1000, v24
	s_nop 0
	v_addc_co_u32_e32 v25, vcc, 0, v25, vcc
	global_load_dword v48, v[24:25], off
	v_add_co_u32_e32 v24, vcc, 0x1000, v24
	s_nop 0
	v_addc_co_u32_e32 v25, vcc, 0, v25, vcc
	global_load_dword v49, v[24:25], off
	v_add_co_u32_e32 v24, vcc, 0x1000, v24
	s_nop 0
	v_addc_co_u32_e32 v25, vcc, 0, v25, vcc
	global_load_dword v50, v[24:25], off
	v_add_co_u32_e32 v24, vcc, 0x1000, v24
	s_nop 0
	v_addc_co_u32_e32 v25, vcc, 0, v25, vcc
	global_load_dword v51, v[24:25], off
	v_add_co_u32_e32 v24, vcc, 0x1000, v24
	s_nop 0
	v_addc_co_u32_e32 v25, vcc, 0, v25, vcc
	global_load_dword v52, v[24:25], off
	v_add_co_u32_e32 v24, vcc, 0x1000, v24
	s_nop 0
	v_addc_co_u32_e32 v25, vcc, 0, v25, vcc
	global_load_dword v53, v[24:25], off
	v_add_co_u32_e32 v24, vcc, 0x1000, v24
	s_nop 0
	v_addc_co_u32_e32 v25, vcc, 0, v25, vcc
	global_load_dword v54, v[24:25], off
	v_add_co_u32_e32 v24, vcc, 0x1000, v24
	s_nop 0
	v_addc_co_u32_e32 v25, vcc, 0, v25, vcc
	global_load_dword v55, v[24:25], off
	v_add_co_u32_e32 v24, vcc, 0x1000, v24
	s_nop 0
	v_addc_co_u32_e32 v25, vcc, 0, v25, vcc
	global_load_dword v56, v[24:25], off
	v_add_co_u32_e32 v24, vcc, 0x1000, v24
	s_nop 0
	v_addc_co_u32_e32 v25, vcc, 0, v25, vcc
	global_load_dword v57, v[24:25], off
	v_add_co_u32_e32 v24, vcc, 0x1000, v24
	s_nop 0
	v_addc_co_u32_e32 v25, vcc, 0, v25, vcc
	global_load_dword v58, v[24:25], off
	v_add_co_u32_e32 v24, vcc, 0x1000, v24
	s_nop 0
	v_addc_co_u32_e32 v25, vcc, 0, v25, vcc
	global_load_dword v59, v[24:25], off
	v_add_co_u32_e32 v24, vcc, 0x1000, v24
	s_nop 0
	v_addc_co_u32_e32 v25, vcc, 0, v25, vcc
	global_load_dword v60, v[24:25], off
	v_add_co_u32_e32 v24, vcc, 0x1000, v24
	s_nop 0
	v_addc_co_u32_e32 v25, vcc, 0, v25, vcc
	global_load_dword v61, v[24:25], off
	v_add_co_u32_e32 v24, vcc, 0x1000, v24
	s_nop 0
	v_addc_co_u32_e32 v25, vcc, 0, v25, vcc
	global_load_dword v62, v[24:25], off
	v_add_co_u32_e32 v24, vcc, 0x1000, v24
	s_nop 0
	v_addc_co_u32_e32 v25, vcc, 0, v25, vcc
	global_load_dword v63, v[24:25], off
	v_add_co_u32_e32 v24, vcc, 0x1000, v24
	s_nop 0
	v_addc_co_u32_e32 v25, vcc, 0, v25, vcc
	global_load_dword v64, v[24:25], off
	v_add_co_u32_e32 v24, vcc, 0x1000, v24
	s_nop 0
	v_addc_co_u32_e32 v25, vcc, 0, v25, vcc
	global_load_dword v65, v[24:25], off
	v_add_co_u32_e32 v24, vcc, 0x1000, v24
	s_nop 0
	v_addc_co_u32_e32 v25, vcc, 0, v25, vcc
	global_load_dword v66, v[24:25], off
	v_add_co_u32_e32 v24, vcc, 0x1000, v24
	s_nop 0
	v_addc_co_u32_e32 v25, vcc, 0, v25, vcc
	global_load_dword v67, v[24:25], off
	v_add_co_u32_e32 v24, vcc, 0x1000, v24
	s_nop 0
	v_addc_co_u32_e32 v25, vcc, 0, v25, vcc
	global_load_dword v68, v[24:25], off
	v_add_co_u32_e32 v24, vcc, 0x1000, v24
	s_nop 0
	v_addc_co_u32_e32 v25, vcc, 0, v25, vcc
	global_load_dword v69, v[24:25], off
	v_add_co_u32_e32 v24, vcc, 0x1000, v24
	s_nop 0
	v_addc_co_u32_e32 v25, vcc, 0, v25, vcc
	global_load_dword v70, v[24:25], off
	v_add_co_u32_e32 v24, vcc, 0x1000, v24
	s_nop 0
	v_addc_co_u32_e32 v25, vcc, 0, v25, vcc
	global_load_dword v71, v[24:25], off
	v_add_co_u32_e32 v24, vcc, 0x1000, v24
	s_nop 0
	v_addc_co_u32_e32 v25, vcc, 0, v25, vcc
	global_load_dword v72, v[24:25], off
	v_add_co_u32_e32 v24, vcc, 0x1000, v24
	s_nop 0
	v_addc_co_u32_e32 v25, vcc, 0, v25, vcc
	global_load_dword v73, v[24:25], off
	v_add_co_u32_e32 v24, vcc, 0x1000, v24
	s_nop 0
	v_addc_co_u32_e32 v25, vcc, 0, v25, vcc
	global_load_dword v74, v[24:25], off
	v_add_co_u32_e32 v24, vcc, 0x1000, v24
	s_nop 0
	v_addc_co_u32_e32 v25, vcc, 0, v25, vcc
	global_load_dword v75, v[24:25], off
	v_add_co_u32_e32 v24, vcc, 0x1000, v24
	s_nop 0
	v_addc_co_u32_e32 v25, vcc, 0, v25, vcc
	global_load_dword v76, v[24:25], off
	v_add_co_u32_e32 v24, vcc, 0x1000, v24
	s_nop 0
	v_addc_co_u32_e32 v25, vcc, 0, v25, vcc
	global_load_dword v77, v[24:25], off
	v_add_co_u32_e32 v24, vcc, 0x1000, v24
	s_nop 0
	v_addc_co_u32_e32 v25, vcc, 0, v25, vcc
	global_load_dword v78, v[24:25], off
	v_add_co_u32_e32 v24, vcc, 0x1000, v24
	s_nop 0
	v_addc_co_u32_e32 v25, vcc, 0, v25, vcc
	global_load_dword v79, v[24:25], off
	v_add_co_u32_e32 v24, vcc, 0x1000, v24
	s_nop 0
	v_addc_co_u32_e32 v25, vcc, 0, v25, vcc
	global_load_dword v80, v[24:25], off
	v_add_co_u32_e32 v24, vcc, 0x1000, v24
	s_nop 0
	v_addc_co_u32_e32 v25, vcc, 0, v25, vcc
	global_load_dword v81, v[24:25], off
	v_add_co_u32_e32 v24, vcc, 0x1000, v24
	s_nop 0
	v_addc_co_u32_e32 v25, vcc, 0, v25, vcc
	global_load_dword v82, v[24:25], off
	v_add_co_u32_e32 v24, vcc, 0x1000, v24
	s_nop 0
	v_addc_co_u32_e32 v25, vcc, 0, v25, vcc
	global_load_dword v83, v[24:25], off
	v_add_co_u32_e32 v24, vcc, 0x1000, v24
	s_nop 0
	v_addc_co_u32_e32 v25, vcc, 0, v25, vcc
	global_load_dword v84, v[24:25], off
	v_add_co_u32_e32 v24, vcc, 0x1000, v24
	s_nop 0
	v_addc_co_u32_e32 v25, vcc, 0, v25, vcc
	global_load_dword v85, v[24:25], off
	v_add_co_u32_e32 v24, vcc, 0x1000, v24
	s_nop 0
	v_addc_co_u32_e32 v25, vcc, 0, v25, vcc
	global_load_dword v86, v[24:25], off
	v_add_co_u32_e32 v24, vcc, 0x1000, v24
	s_nop 0
	v_addc_co_u32_e32 v25, vcc, 0, v25, vcc
	global_load_dword v87, v[24:25], off
	v_add_co_u32_e32 v24, vcc, 0x1000, v24
	s_nop 0
	v_addc_co_u32_e32 v25, vcc, 0, v25, vcc
	global_load_dword v88, v[24:25], off
	v_add_co_u32_e32 v24, vcc, 0x1000, v24
	s_nop 0
	v_addc_co_u32_e32 v25, vcc, 0, v25, vcc
	global_load_dword v89, v[24:25], off
	v_add_co_u32_e32 v24, vcc, 0x1000, v24
	s_nop 0
	v_addc_co_u32_e32 v25, vcc, 0, v25, vcc
	global_load_dword v90, v[24:25], off
	v_add_co_u32_e32 v24, vcc, 0x1000, v24
	s_nop 0
	v_addc_co_u32_e32 v25, vcc, 0, v25, vcc
	global_load_dword v91, v[24:25], off
	v_add_co_u32_e32 v24, vcc, 0x1000, v24
	s_nop 0
	v_addc_co_u32_e32 v25, vcc, 0, v25, vcc
	global_load_dword v92, v[24:25], off
	v_add_co_u32_e32 v24, vcc, 0x1000, v24
	s_nop 0
	v_addc_co_u32_e32 v25, vcc, 0, v25, vcc
	global_load_dword v93, v[24:25], off
	v_add_co_u32_e32 v24, vcc, 0x1000, v24
	s_nop 0
	v_addc_co_u32_e32 v25, vcc, 0, v25, vcc
	global_load_dword v94, v[24:25], off
	v_add_co_u32_e32 v24, vcc, 0x1000, v24
	s_nop 0
	v_addc_co_u32_e32 v25, vcc, 0, v25, vcc
	s_waitcnt vmcnt(62)
	global_load_dword v95, v[24:25], off
	s_waitcnt vmcnt(56)
	v_cvt_pk_bf16_f32 v6, v32, v33
	v_cvt_pk_bf16_f32 v7, v34, v35
	v_cvt_pk_bf16_f32 v8, v36, v37
	v_cvt_pk_bf16_f32 v9, v38, v39
	ds_write_b128 v0, v[6:9]
	s_waitcnt vmcnt(48)
	v_cvt_pk_bf16_f32 v6, v40, v41
	v_cvt_pk_bf16_f32 v7, v42, v43
	v_cvt_pk_bf16_f32 v8, v44, v45
	v_cvt_pk_bf16_f32 v9, v46, v47
	ds_write_b128 v0, v[6:9] offset:16
	s_waitcnt vmcnt(40)
	v_cvt_pk_bf16_f32 v6, v48, v49
	v_cvt_pk_bf16_f32 v7, v50, v51
	v_cvt_pk_bf16_f32 v8, v52, v53
	v_cvt_pk_bf16_f32 v9, v54, v55
	ds_write_b128 v0, v[6:9] offset:32
	s_waitcnt vmcnt(32)
	v_cvt_pk_bf16_f32 v6, v56, v57
	v_cvt_pk_bf16_f32 v7, v58, v59
	v_cvt_pk_bf16_f32 v8, v60, v61
	v_cvt_pk_bf16_f32 v9, v62, v63
	ds_write_b128 v0, v[6:9] offset:48
	s_waitcnt vmcnt(24)
	v_cvt_pk_bf16_f32 v6, v64, v65
	v_cvt_pk_bf16_f32 v7, v66, v67
	v_cvt_pk_bf16_f32 v8, v68, v69
	v_cvt_pk_bf16_f32 v9, v70, v71
	ds_write_b128 v0, v[6:9] offset:64
	s_waitcnt vmcnt(16)
	v_cvt_pk_bf16_f32 v6, v72, v73
	v_cvt_pk_bf16_f32 v7, v74, v75
	v_cvt_pk_bf16_f32 v8, v76, v77
	v_cvt_pk_bf16_f32 v9, v78, v79
	ds_write_b128 v0, v[6:9] offset:80
	s_waitcnt vmcnt(8)
	v_cvt_pk_bf16_f32 v6, v80, v81
	v_cvt_pk_bf16_f32 v7, v82, v83
	v_cvt_pk_bf16_f32 v8, v84, v85
	v_cvt_pk_bf16_f32 v9, v86, v87
	ds_write_b128 v0, v[6:9] offset:96
	s_waitcnt vmcnt(0)
	v_cvt_pk_bf16_f32 v6, v88, v89
	v_cvt_pk_bf16_f32 v7, v90, v91
	v_cvt_pk_bf16_f32 v8, v92, v93
	v_cvt_pk_bf16_f32 v9, v94, v95
	ds_write_b128 v0, v[6:9] offset:112
	s_mov_b32 s8, 0x3f000
	v_add_u32_e32 v3, 0x100, v2
	v_ashrrev_i32_e32 v10, 3, v2
	v_ashrrev_i32_e32 v11, 31, v10
	v_lshlrev_b32_e32 v0, 4, v2
	v_and_b32_e32 v0, 0x70, v0
	v_lshl_add_u64 v[8:9], s[0:1], 0, v[0:1]
	v_mad_u64_u32 v[4:5], s[0:1], v10, s9, v[0:1]
	s_waitcnt lgkmcnt(0)
	s_barrier
	ds_read_b128 v[4:7], v4
	v_lshlrev_b64 v[10:11], 11, v[10:11]
	v_lshl_add_u64 v[10:11], v[8:9], 0, v[10:11]
	s_waitcnt lgkmcnt(0)
	global_store_dwordx4 v[10:11], v[4:7], off
	v_ashrrev_i32_e32 v10, 3, v3
	s_nop 0
	v_mad_u64_u32 v[4:5], s[0:1], v10, s9, v[0:1]
	ds_read_b128 v[4:7], v4
	v_ashrrev_i32_e32 v11, 31, v10
	v_lshlrev_b64 v[10:11], 11, v[10:11]
	v_lshl_add_u64 v[10:11], v[8:9], 0, v[10:11]
	v_add_u32_e32 v3, 0x200, v2
	s_waitcnt lgkmcnt(0)
	global_store_dwordx4 v[10:11], v[4:7], off
	v_ashrrev_i32_e32 v10, 3, v3
	v_ashrrev_i32_e32 v11, 31, v10
	v_mad_u64_u32 v[4:5], s[0:1], v10, s9, v[0:1]
	ds_read_b128 v[4:7], v4
	v_lshlrev_b64 v[10:11], 11, v[10:11]
	v_lshl_add_u64 v[10:11], v[8:9], 0, v[10:11]
	v_add_u32_e32 v3, 0x300, v2
	s_waitcnt lgkmcnt(0)
	global_store_dwordx4 v[10:11], v[4:7], off
	v_ashrrev_i32_e32 v10, 3, v3
	s_nop 0
	v_mad_u64_u32 v[4:5], s[0:1], v10, s9, v[0:1]
	ds_read_b128 v[4:7], v4
	v_ashrrev_i32_e32 v11, 31, v10
	v_lshlrev_b64 v[10:11], 11, v[10:11]
	v_lshl_add_u64 v[10:11], v[8:9], 0, v[10:11]
	v_add_u32_e32 v3, 0x400, v2
	s_waitcnt lgkmcnt(0)
	global_store_dwordx4 v[10:11], v[4:7], off
	v_ashrrev_i32_e32 v10, 3, v3
	v_ashrrev_i32_e32 v11, 31, v10
	v_mad_u64_u32 v[4:5], s[0:1], v10, s9, v[0:1]
	ds_read_b128 v[4:7], v4
	v_lshlrev_b64 v[10:11], 11, v[10:11]
	v_lshl_add_u64 v[10:11], v[8:9], 0, v[10:11]
	v_add_u32_e32 v3, 0x500, v2
	s_waitcnt lgkmcnt(0)
	global_store_dwordx4 v[10:11], v[4:7], off
	v_ashrrev_i32_e32 v10, 3, v3
	s_nop 0
	v_mad_u64_u32 v[4:5], s[0:1], v10, s9, v[0:1]
	ds_read_b128 v[4:7], v4
	v_ashrrev_i32_e32 v11, 31, v10
	v_lshlrev_b64 v[10:11], 11, v[10:11]
	v_lshl_add_u64 v[10:11], v[8:9], 0, v[10:11]
	v_add_u32_e32 v3, 0x600, v2
	s_waitcnt lgkmcnt(0)
	global_store_dwordx4 v[10:11], v[4:7], off
	v_ashrrev_i32_e32 v10, 3, v3
	v_ashrrev_i32_e32 v11, 31, v10
	v_mad_u64_u32 v[4:5], s[0:1], v10, s9, v[0:1]
	ds_read_b128 v[4:7], v4
	v_lshlrev_b64 v[10:11], 11, v[10:11]
	v_lshl_add_u64 v[10:11], v[8:9], 0, v[10:11]
	v_add_u32_e32 v2, 0x700, v2
	s_waitcnt lgkmcnt(0)
	global_store_dwordx4 v[10:11], v[4:7], off
	s_nop 1
	v_ashrrev_i32_e32 v6, 3, v2
	v_mad_u64_u32 v[2:3], s[0:1], v6, s9, v[0:1]
	ds_read_b128 v[2:5], v2
	v_ashrrev_i32_e32 v7, 31, v6
	v_lshlrev_b64 v[6:7], 11, v[6:7]
	v_lshl_add_u64 v[6:7], v[8:9], 0, v[6:7]
	s_waitcnt lgkmcnt(0)
	global_store_dwordx4 v[6:7], v[2:5], off

.LBB0_806:
	s_andn2_b64 vcc, exec, s[0:1]
	s_cbranch_vccnz .LBB0_813
	s_add_i32 s8, s7, 0xfffffe30
	s_cmpk_gt_u32 s8, 0xcf
	s_cselect_b64 s[0:1], -1, 0
	s_add_i32 s9, s7, 0x60
	s_cmpk_lt_u32 s8, 0xd0
	s_cselect_b32 s9, s8, s9
	s_and_b32 s8, s9, 0xff
	s_mulk_i32 s8, 0x4f
	s_lshr_b32 s8, s8, 10
	s_mul_i32 s10, s8, 13
	s_sub_i32 s9, s9, s10
	s_and_b32 s9, s9, 0xff
	s_and_b64 s[10:11], s[0:1], exec
	v_readlane_b32 s52, v252, 29
	s_cselect_b32 s10, 0xd00000, 0
	v_readlane_b32 s60, v252, 37
	v_readlane_b32 s61, v252, 38
	s_add_u32 s10, s60, s10
	s_addc_u32 s11, s61, 0
	s_mul_i32 s12, s8, 0xd0000
	s_add_u32 s10, s10, s12
	s_addc_u32 s11, s11, 0
	s_lshl_b32 s12, s9, 10
	s_add_u32 s28, s10, s12
	s_addc_u32 s29, s11, 0
	s_cmp_lg_u32 s9, 11
	s_mov_b64 s[38:39], -1
	v_readlane_b32 s53, v252, 30
	v_readlane_b32 s54, v252, 31
	v_readlane_b32 s55, v252, 32
	v_readlane_b32 s56, v252, 33
	v_readlane_b32 s57, v252, 34
	v_readlane_b32 s58, v252, 35
	v_readlane_b32 s59, v252, 36
	v_readlane_b32 s62, v252, 39
	v_readlane_b32 s63, v252, 40
	v_readlane_b32 s64, v252, 41
	v_readlane_b32 s65, v252, 42
	v_readlane_b32 s66, v252, 43
	v_readlane_b32 s67, v252, 44
	s_cbranch_scc0 .LBB0_809
	s_and_b64 s[10:11], s[0:1], exec
	s_cselect_b32 s10, 0x700000, 0
	v_readlane_b32 s11, v253, 30
	s_add_u32 s10, s11, s10
	v_readlane_b32 s11, v253, 31
	s_addc_u32 s11, s11, 0
	s_lshl_b32 s12, s9, 18
	s_add_i32 s13, s12, 0x40000
	s_cmp_lt_u32 s9, 11
	s_cselect_b32 s9, s12, s13
	v_mov_b32_e32 v2, v151
	s_lshl_b32 s9, s9, 1
	s_add_u32 s9, s10, s9
	v_ashrrev_i32_e32 v3, 31, v2
	v_lshl_add_u64 v[4:5], v[2:3], 2, s[28:29]
	s_addc_u32 s10, s11, 0
	s_lshl_b32 s11, s8, 7
	v_add_co_u32_e32 v6, vcc, s50, v4
	s_add_u32 s38, s9, s11
	s_nop 0
	v_addc_co_u32_e32 v7, vcc, 0, v5, vcc
	s_movk_i32 s9, 0x6000
	s_waitcnt vmcnt(63) expcnt(7) lgkmcnt(15)
	s_barrier
	s_movk_i32 s12, 0x90
	v_mul_lo_u32 v0, v2, s12
	s_addc_u32 s39, s10, 0
	v_mov_b32_e32 v24, v4
	v_mov_b32_e32 v25, v5
	global_load_dword v32, v[24:25], off
	v_add_co_u32_e32 v24, vcc, 0x3400, v24
	s_nop 0
	v_addc_co_u32_e32 v25, vcc, 0, v25, vcc
	global_load_dword v33, v[24:25], off
	v_add_co_u32_e32 v24, vcc, 0x3400, v24
	s_nop 0
	v_addc_co_u32_e32 v25, vcc, 0, v25, vcc
	global_load_dword v34, v[24:25], off
	v_add_co_u32_e32 v24, vcc, 0x3400, v24
	s_nop 0
	v_addc_co_u32_e32 v25, vcc, 0, v25, vcc
	global_load_dword v35, v[24:25], off
	v_add_co_u32_e32 v24, vcc, 0x3400, v24
	s_nop 0
	v_addc_co_u32_e32 v25, vcc, 0, v25, vcc
	global_load_dword v36, v[24:25], off
	v_add_co_u32_e32 v24, vcc, 0x3400, v24
	s_nop 0
	v_addc_co_u32_e32 v25, vcc, 0, v25, vcc
	global_load_dword v37, v[24:25], off
	v_add_co_u32_e32 v24, vcc, 0x3400, v24
	s_nop 0
	v_addc_co_u32_e32 v25, vcc, 0, v25, vcc
	global_load_dword v38, v[24:25], off
	v_add_co_u32_e32 v24, vcc, 0x3400, v24
	s_nop 0
	v_addc_co_u32_e32 v25, vcc, 0, v25, vcc
	global_load_dword v39, v[24:25], off
	v_add_co_u32_e32 v24, vcc, 0x3400, v24
	s_nop 0
	v_addc_co_u32_e32 v25, vcc, 0, v25, vcc
	global_load_dword v40, v[24:25], off
	v_add_co_u32_e32 v24, vcc, 0x3400, v24
	s_nop 0
	v_addc_co_u32_e32 v25, vcc, 0, v25, vcc
	global_load_dword v41, v[24:25], off
	v_add_co_u32_e32 v24, vcc, 0x3400, v24
	s_nop 0
	v_addc_co_u32_e32 v25, vcc, 0, v25, vcc
	global_load_dword v42, v[24:25], off
	v_add_co_u32_e32 v24, vcc, 0x3400, v24
	s_nop 0
	v_addc_co_u32_e32 v25, vcc, 0, v25, vcc
	global_load_dword v43, v[24:25], off
	v_add_co_u32_e32 v24, vcc, 0x3400, v24
	s_nop 0
	v_addc_co_u32_e32 v25, vcc, 0, v25, vcc
	global_load_dword v44, v[24:25], off
	v_add_co_u32_e32 v24, vcc, 0x3400, v24
	s_nop 0
	v_addc_co_u32_e32 v25, vcc, 0, v25, vcc
	global_load_dword v45, v[24:25], off
	v_add_co_u32_e32 v24, vcc, 0x3400, v24
	s_nop 0
	v_addc_co_u32_e32 v25, vcc, 0, v25, vcc
	global_load_dword v46, v[24:25], off
	v_add_co_u32_e32 v24, vcc, 0x3400, v24
	s_nop 0
	v_addc_co_u32_e32 v25, vcc, 0, v25, vcc
	global_load_dword v47, v[24:25], off
	v_add_co_u32_e32 v24, vcc, 0x3400, v24
	s_nop 0
	v_addc_co_u32_e32 v25, vcc, 0, v25, vcc
	global_load_dword v48, v[24:25], off
	v_add_co_u32_e32 v24, vcc, 0x3400, v24
	s_nop 0
	v_addc_co_u32_e32 v25, vcc, 0, v25, vcc
	global_load_dword v49, v[24:25], off
	v_add_co_u32_e32 v24, vcc, 0x3400, v24
	s_nop 0
	v_addc_co_u32_e32 v25, vcc, 0, v25, vcc
	global_load_dword v50, v[24:25], off
	v_add_co_u32_e32 v24, vcc, 0x3400, v24
	s_nop 0
	v_addc_co_u32_e32 v25, vcc, 0, v25, vcc
	global_load_dword v51, v[24:25], off
	v_add_co_u32_e32 v24, vcc, 0x3400, v24
	s_nop 0
	v_addc_co_u32_e32 v25, vcc, 0, v25, vcc
	global_load_dword v52, v[24:25], off
	v_add_co_u32_e32 v24, vcc, 0x3400, v24
	s_nop 0
	v_addc_co_u32_e32 v25, vcc, 0, v25, vcc
	global_load_dword v53, v[24:25], off
	v_add_co_u32_e32 v24, vcc, 0x3400, v24
	s_nop 0
	v_addc_co_u32_e32 v25, vcc, 0, v25, vcc
	global_load_dword v54, v[24:25], off
	v_add_co_u32_e32 v24, vcc, 0x3400, v24
	s_nop 0
	v_addc_co_u32_e32 v25, vcc, 0, v25, vcc
	global_load_dword v55, v[24:25], off
	v_add_co_u32_e32 v24, vcc, 0x3400, v24
	s_nop 0
	v_addc_co_u32_e32 v25, vcc, 0, v25, vcc
	global_load_dword v56, v[24:25], off
	v_add_co_u32_e32 v24, vcc, 0x3400, v24
	s_nop 0
	v_addc_co_u32_e32 v25, vcc, 0, v25, vcc
	global_load_dword v57, v[24:25], off
	v_add_co_u32_e32 v24, vcc, 0x3400, v24
	s_nop 0
	v_addc_co_u32_e32 v25, vcc, 0, v25, vcc
	global_load_dword v58, v[24:25], off
	v_add_co_u32_e32 v24, vcc, 0x3400, v24
	s_nop 0
	v_addc_co_u32_e32 v25, vcc, 0, v25, vcc
	global_load_dword v59, v[24:25], off
	v_add_co_u32_e32 v24, vcc, 0x3400, v24
	s_nop 0
	v_addc_co_u32_e32 v25, vcc, 0, v25, vcc
	global_load_dword v60, v[24:25], off
	v_add_co_u32_e32 v24, vcc, 0x3400, v24
	s_nop 0
	v_addc_co_u32_e32 v25, vcc, 0, v25, vcc
	global_load_dword v61, v[24:25], off
	v_add_co_u32_e32 v24, vcc, 0x3400, v24
	s_nop 0
	v_addc_co_u32_e32 v25, vcc, 0, v25, vcc
	global_load_dword v62, v[24:25], off
	v_add_co_u32_e32 v24, vcc, 0x3400, v24
	s_nop 0
	v_addc_co_u32_e32 v25, vcc, 0, v25, vcc
	global_load_dword v63, v[24:25], off
	v_add_co_u32_e32 v24, vcc, 0x3400, v24
	s_nop 0
	v_addc_co_u32_e32 v25, vcc, 0, v25, vcc
	global_load_dword v64, v[24:25], off
	v_add_co_u32_e32 v24, vcc, 0x3400, v24
	s_nop 0
	v_addc_co_u32_e32 v25, vcc, 0, v25, vcc
	global_load_dword v65, v[24:25], off
	v_add_co_u32_e32 v24, vcc, 0x3400, v24
	s_nop 0
	v_addc_co_u32_e32 v25, vcc, 0, v25, vcc
	global_load_dword v66, v[24:25], off
	v_add_co_u32_e32 v24, vcc, 0x3400, v24
	s_nop 0
	v_addc_co_u32_e32 v25, vcc, 0, v25, vcc
	global_load_dword v67, v[24:25], off
	v_add_co_u32_e32 v24, vcc, 0x3400, v24
	s_nop 0
	v_addc_co_u32_e32 v25, vcc, 0, v25, vcc
	global_load_dword v68, v[24:25], off
	v_add_co_u32_e32 v24, vcc, 0x3400, v24
	s_nop 0
	v_addc_co_u32_e32 v25, vcc, 0, v25, vcc
	global_load_dword v69, v[24:25], off
	v_add_co_u32_e32 v24, vcc, 0x3400, v24
	s_nop 0
	v_addc_co_u32_e32 v25, vcc, 0, v25, vcc
	global_load_dword v70, v[24:25], off
	v_add_co_u32_e32 v24, vcc, 0x3400, v24
	s_nop 0
	v_addc_co_u32_e32 v25, vcc, 0, v25, vcc
	global_load_dword v71, v[24:25], off
	v_add_co_u32_e32 v24, vcc, 0x3400, v24
	s_nop 0
	v_addc_co_u32_e32 v25, vcc, 0, v25, vcc
	global_load_dword v72, v[24:25], off
	v_add_co_u32_e32 v24, vcc, 0x3400, v24
	s_nop 0
	v_addc_co_u32_e32 v25, vcc, 0, v25, vcc
	global_load_dword v73, v[24:25], off
	v_add_co_u32_e32 v24, vcc, 0x3400, v24
	s_nop 0
	v_addc_co_u32_e32 v25, vcc, 0, v25, vcc
	global_load_dword v74, v[24:25], off
	v_add_co_u32_e32 v24, vcc, 0x3400, v24
	s_nop 0
	v_addc_co_u32_e32 v25, vcc, 0, v25, vcc
	global_load_dword v75, v[24:25], off
	v_add_co_u32_e32 v24, vcc, 0x3400, v24
	s_nop 0
	v_addc_co_u32_e32 v25, vcc, 0, v25, vcc
	global_load_dword v76, v[24:25], off
	v_add_co_u32_e32 v24, vcc, 0x3400, v24
	s_nop 0
	v_addc_co_u32_e32 v25, vcc, 0, v25, vcc
	global_load_dword v77, v[24:25], off
	v_add_co_u32_e32 v24, vcc, 0x3400, v24
	s_nop 0
	v_addc_co_u32_e32 v25, vcc, 0, v25, vcc
	global_load_dword v78, v[24:25], off
	v_add_co_u32_e32 v24, vcc, 0x3400, v24
	s_nop 0
	v_addc_co_u32_e32 v25, vcc, 0, v25, vcc
	global_load_dword v79, v[24:25], off
	v_add_co_u32_e32 v24, vcc, 0x3400, v24
	s_nop 0
	v_addc_co_u32_e32 v25, vcc, 0, v25, vcc
	global_load_dword v80, v[24:25], off
	v_add_co_u32_e32 v24, vcc, 0x3400, v24
	s_nop 0
	v_addc_co_u32_e32 v25, vcc, 0, v25, vcc
	global_load_dword v81, v[24:25], off
	v_add_co_u32_e32 v24, vcc, 0x3400, v24
	s_nop 0
	v_addc_co_u32_e32 v25, vcc, 0, v25, vcc
	global_load_dword v82, v[24:25], off
	v_add_co_u32_e32 v24, vcc, 0x3400, v24
	s_nop 0
	v_addc_co_u32_e32 v25, vcc, 0, v25, vcc
	global_load_dword v83, v[24:25], off
	v_add_co_u32_e32 v24, vcc, 0x3400, v24
	s_nop 0
	v_addc_co_u32_e32 v25, vcc, 0, v25, vcc
	global_load_dword v84, v[24:25], off
	v_add_co_u32_e32 v24, vcc, 0x3400, v24
	s_nop 0
	v_addc_co_u32_e32 v25, vcc, 0, v25, vcc
	global_load_dword v85, v[24:25], off
	v_add_co_u32_e32 v24, vcc, 0x3400, v24
	s_nop 0
	v_addc_co_u32_e32 v25, vcc, 0, v25, vcc
	global_load_dword v86, v[24:25], off
	v_add_co_u32_e32 v24, vcc, 0x3400, v24
	s_nop 0
	v_addc_co_u32_e32 v25, vcc, 0, v25, vcc
	global_load_dword v87, v[24:25], off
	v_add_co_u32_e32 v24, vcc, 0x3400, v24
	s_nop 0
	v_addc_co_u32_e32 v25, vcc, 0, v25, vcc
	global_load_dword v88, v[24:25], off
	v_add_co_u32_e32 v24, vcc, 0x3400, v24
	s_nop 0
	v_addc_co_u32_e32 v25, vcc, 0, v25, vcc
	global_load_dword v89, v[24:25], off
	v_add_co_u32_e32 v24, vcc, 0x3400, v24
	s_nop 0
	v_addc_co_u32_e32 v25, vcc, 0, v25, vcc
	global_load_dword v90, v[24:25], off
	v_add_co_u32_e32 v24, vcc, 0x3400, v24
	s_nop 0
	v_addc_co_u32_e32 v25, vcc, 0, v25, vcc
	global_load_dword v91, v[24:25], off
	v_add_co_u32_e32 v24, vcc, 0x3400, v24
	s_nop 0
	v_addc_co_u32_e32 v25, vcc, 0, v25, vcc
	global_load_dword v92, v[24:25], off
	v_add_co_u32_e32 v24, vcc, 0x3400, v24
	s_nop 0
	v_addc_co_u32_e32 v25, vcc, 0, v25, vcc
	global_load_dword v93, v[24:25], off
	v_add_co_u32_e32 v24, vcc, 0x3400, v24
	s_nop 0
	v_addc_co_u32_e32 v25, vcc, 0, v25, vcc
	global_load_dword v94, v[24:25], off
	v_add_co_u32_e32 v24, vcc, 0x3400, v24
	s_nop 0
	v_addc_co_u32_e32 v25, vcc, 0, v25, vcc
	s_waitcnt vmcnt(62)
	global_load_dword v95, v[24:25], off
	s_waitcnt vmcnt(56)
	v_cvt_pk_bf16_f32 v6, v32, v33
	v_cvt_pk_bf16_f32 v7, v34, v35
	v_cvt_pk_bf16_f32 v8, v36, v37
	v_cvt_pk_bf16_f32 v9, v38, v39
	ds_write_b128 v0, v[6:9]
	s_waitcnt vmcnt(48)
	v_cvt_pk_bf16_f32 v6, v40, v41
	v_cvt_pk_bf16_f32 v7, v42, v43
	v_cvt_pk_bf16_f32 v8, v44, v45
	v_cvt_pk_bf16_f32 v9, v46, v47
	ds_write_b128 v0, v[6:9] offset:16
	s_waitcnt vmcnt(40)
	v_cvt_pk_bf16_f32 v6, v48, v49
	v_cvt_pk_bf16_f32 v7, v50, v51
	v_cvt_pk_bf16_f32 v8, v52, v53
	v_cvt_pk_bf16_f32 v9, v54, v55
	ds_write_b128 v0, v[6:9] offset:32
	s_waitcnt vmcnt(32)
	v_cvt_pk_bf16_f32 v6, v56, v57
	v_cvt_pk_bf16_f32 v7, v58, v59
	v_cvt_pk_bf16_f32 v8, v60, v61
	v_cvt_pk_bf16_f32 v9, v62, v63
	ds_write_b128 v0, v[6:9] offset:48
	s_waitcnt vmcnt(24)
	v_cvt_pk_bf16_f32 v6, v64, v65
	v_cvt_pk_bf16_f32 v7, v66, v67
	v_cvt_pk_bf16_f32 v8, v68, v69
	v_cvt_pk_bf16_f32 v9, v70, v71
	ds_write_b128 v0, v[6:9] offset:64
	s_waitcnt vmcnt(16)
	v_cvt_pk_bf16_f32 v6, v72, v73
	v_cvt_pk_bf16_f32 v7, v74, v75
	v_cvt_pk_bf16_f32 v8, v76, v77
	v_cvt_pk_bf16_f32 v9, v78, v79
	ds_write_b128 v0, v[6:9] offset:80
	s_waitcnt vmcnt(8)
	v_cvt_pk_bf16_f32 v6, v80, v81
	v_cvt_pk_bf16_f32 v7, v82, v83
	v_cvt_pk_bf16_f32 v8, v84, v85
	v_cvt_pk_bf16_f32 v9, v86, v87
	ds_write_b128 v0, v[6:9] offset:96
	s_waitcnt vmcnt(0)
	v_cvt_pk_bf16_f32 v6, v88, v89
	v_cvt_pk_bf16_f32 v7, v90, v91
	v_cvt_pk_bf16_f32 v8, v92, v93
	v_cvt_pk_bf16_f32 v9, v94, v95
	ds_write_b128 v0, v[6:9] offset:112
	v_add_u32_e32 v3, 0x100, v2
	v_ashrrev_i32_e32 v10, 3, v2
	v_ashrrev_i32_e32 v11, 31, v10
	v_lshlrev_b32_e32 v0, 4, v2
	v_and_b32_e32 v0, 0x70, v0
	v_mad_u64_u32 v[4:5], s[10:11], v10, s12, v[0:1]
	s_waitcnt lgkmcnt(0)
	s_barrier
	ds_read_b128 v[4:7], v4
	v_lshl_add_u64 v[8:9], s[38:39], 0, v[0:1]
	v_lshlrev_b64 v[10:11], 11, v[10:11]
	v_lshl_add_u64 v[10:11], v[8:9], 0, v[10:11]
	s_mov_b64 s[38:39], 0
	s_waitcnt lgkmcnt(0)
	global_store_dwordx4 v[10:11], v[4:7], off
	v_ashrrev_i32_e32 v10, 3, v3
	v_ashrrev_i32_e32 v11, 31, v10
	v_mad_u64_u32 v[4:5], s[10:11], v10, s12, v[0:1]
	ds_read_b128 v[4:7], v4
	v_lshlrev_b64 v[10:11], 11, v[10:11]
	v_lshl_add_u64 v[10:11], v[8:9], 0, v[10:11]
	v_add_u32_e32 v3, 0x200, v2
	s_waitcnt lgkmcnt(0)
	global_store_dwordx4 v[10:11], v[4:7], off
	v_ashrrev_i32_e32 v10, 3, v3
	s_nop 0
	v_mad_u64_u32 v[4:5], s[10:11], v10, s12, v[0:1]
	ds_read_b128 v[4:7], v4
	v_ashrrev_i32_e32 v11, 31, v10
	v_lshlrev_b64 v[10:11], 11, v[10:11]
	v_lshl_add_u64 v[10:11], v[8:9], 0, v[10:11]
	v_add_u32_e32 v3, 0x300, v2
	s_waitcnt lgkmcnt(0)
	global_store_dwordx4 v[10:11], v[4:7], off
	v_ashrrev_i32_e32 v10, 3, v3
	v_ashrrev_i32_e32 v11, 31, v10
	v_mad_u64_u32 v[4:5], s[10:11], v10, s12, v[0:1]
	ds_read_b128 v[4:7], v4
	v_lshlrev_b64 v[10:11], 11, v[10:11]
	v_lshl_add_u64 v[10:11], v[8:9], 0, v[10:11]
	v_add_u32_e32 v3, 0x400, v2
	s_waitcnt lgkmcnt(0)
	global_store_dwordx4 v[10:11], v[4:7], off
	v_ashrrev_i32_e32 v10, 3, v3
	s_nop 0
	v_mad_u64_u32 v[4:5], s[10:11], v10, s12, v[0:1]
	ds_read_b128 v[4:7], v4
	v_ashrrev_i32_e32 v11, 31, v10
	v_lshlrev_b64 v[10:11], 11, v[10:11]
	v_lshl_add_u64 v[10:11], v[8:9], 0, v[10:11]
	v_add_u32_e32 v3, 0x500, v2
	s_waitcnt lgkmcnt(0)
	global_store_dwordx4 v[10:11], v[4:7], off
	v_ashrrev_i32_e32 v10, 3, v3
	v_ashrrev_i32_e32 v11, 31, v10
	v_mad_u64_u32 v[4:5], s[10:11], v10, s12, v[0:1]
	ds_read_b128 v[4:7], v4
	v_lshlrev_b64 v[10:11], 11, v[10:11]
	v_lshl_add_u64 v[10:11], v[8:9], 0, v[10:11]
	v_add_u32_e32 v3, 0x600, v2
	v_add_u32_e32 v2, 0x700, v2
	s_waitcnt lgkmcnt(0)
	global_store_dwordx4 v[10:11], v[4:7], off
	v_ashrrev_i32_e32 v10, 3, v3
	v_ashrrev_i32_e32 v11, 31, v10
	v_mad_u64_u32 v[4:5], s[10:11], v10, s12, v[0:1]
	ds_read_b128 v[4:7], v4
	v_lshlrev_b64 v[10:11], 11, v[10:11]
	v_lshl_add_u64 v[10:11], v[8:9], 0, v[10:11]
	s_waitcnt lgkmcnt(0)
	global_store_dwordx4 v[10:11], v[4:7], off
	s_nop 1
	v_ashrrev_i32_e32 v6, 3, v2
	v_mad_u64_u32 v[2:3], s[10:11], v6, s12, v[0:1]
	ds_read_b128 v[2:5], v2
	v_ashrrev_i32_e32 v7, 31, v6
	v_lshlrev_b64 v[6:7], 11, v[6:7]
	v_lshl_add_u64 v[6:7], v[8:9], 0, v[6:7]
	s_waitcnt lgkmcnt(0)
	global_store_dwordx4 v[6:7], v[2:5], off

.LBB0_811:
	v_mov_b32_e32 v6, v2
	v_mov_b32_e32 v7, v3
	global_load_dword v32, v[6:7], off
	v_add_co_u32_e32 v6, vcc, 0x3400, v6
	s_nop 0
	v_addc_co_u32_e32 v7, vcc, 0, v7, vcc
	global_load_dword v33, v[6:7], off
	v_add_co_u32_e32 v6, vcc, 0x3400, v6
	s_nop 0
	v_addc_co_u32_e32 v7, vcc, 0, v7, vcc
	global_load_dword v34, v[6:7], off
	v_add_co_u32_e32 v6, vcc, 0x3400, v6
	s_nop 0
	v_addc_co_u32_e32 v7, vcc, 0, v7, vcc
	global_load_dword v35, v[6:7], off
	v_add_co_u32_e32 v6, vcc, 0x3400, v6
	s_nop 0
	v_addc_co_u32_e32 v7, vcc, 0, v7, vcc
	global_load_dword v36, v[6:7], off
	v_add_co_u32_e32 v6, vcc, 0x3400, v6
	s_nop 0
	v_addc_co_u32_e32 v7, vcc, 0, v7, vcc
	global_load_dword v37, v[6:7], off
	v_add_co_u32_e32 v6, vcc, 0x3400, v6
	s_nop 0
	v_addc_co_u32_e32 v7, vcc, 0, v7, vcc
	global_load_dword v38, v[6:7], off
	v_add_co_u32_e32 v6, vcc, 0x3400, v6
	s_nop 0
	v_addc_co_u32_e32 v7, vcc, 0, v7, vcc
	global_load_dword v39, v[6:7], off
	v_add_co_u32_e32 v6, vcc, 0x3400, v6
	s_nop 0
	v_addc_co_u32_e32 v7, vcc, 0, v7, vcc
	global_load_dword v40, v[6:7], off
	v_add_co_u32_e32 v6, vcc, 0x3400, v6
	s_nop 0
	v_addc_co_u32_e32 v7, vcc, 0, v7, vcc
	global_load_dword v41, v[6:7], off
	v_add_co_u32_e32 v6, vcc, 0x3400, v6
	s_nop 0
	v_addc_co_u32_e32 v7, vcc, 0, v7, vcc
	global_load_dword v42, v[6:7], off
	v_add_co_u32_e32 v6, vcc, 0x3400, v6
	s_nop 0
	v_addc_co_u32_e32 v7, vcc, 0, v7, vcc
	global_load_dword v43, v[6:7], off
	v_add_co_u32_e32 v6, vcc, 0x3400, v6
	s_nop 0
	v_addc_co_u32_e32 v7, vcc, 0, v7, vcc
	global_load_dword v44, v[6:7], off
	v_add_co_u32_e32 v6, vcc, 0x3400, v6
	s_nop 0
	v_addc_co_u32_e32 v7, vcc, 0, v7, vcc
	global_load_dword v45, v[6:7], off
	v_add_co_u32_e32 v6, vcc, 0x3400, v6
	s_nop 0
	v_addc_co_u32_e32 v7, vcc, 0, v7, vcc
	global_load_dword v46, v[6:7], off
	v_add_co_u32_e32 v6, vcc, 0x3400, v6
	s_nop 0
	v_addc_co_u32_e32 v7, vcc, 0, v7, vcc
	global_load_dword v47, v[6:7], off
	v_add_co_u32_e32 v6, vcc, 0x3400, v6
	s_nop 0
	v_addc_co_u32_e32 v7, vcc, 0, v7, vcc
	global_load_dword v48, v[6:7], off
	v_add_co_u32_e32 v6, vcc, 0x3400, v6
	s_nop 0
	v_addc_co_u32_e32 v7, vcc, 0, v7, vcc
	global_load_dword v49, v[6:7], off
	v_add_co_u32_e32 v6, vcc, 0x3400, v6
	s_nop 0
	v_addc_co_u32_e32 v7, vcc, 0, v7, vcc
	global_load_dword v50, v[6:7], off
	v_add_co_u32_e32 v6, vcc, 0x3400, v6
	s_nop 0
	v_addc_co_u32_e32 v7, vcc, 0, v7, vcc
	global_load_dword v51, v[6:7], off
	v_add_co_u32_e32 v6, vcc, 0x3400, v6
	s_nop 0
	v_addc_co_u32_e32 v7, vcc, 0, v7, vcc
	global_load_dword v52, v[6:7], off
	v_add_co_u32_e32 v6, vcc, 0x3400, v6
	s_nop 0
	v_addc_co_u32_e32 v7, vcc, 0, v7, vcc
	global_load_dword v53, v[6:7], off
	v_add_co_u32_e32 v6, vcc, 0x3400, v6
	s_nop 0
	v_addc_co_u32_e32 v7, vcc, 0, v7, vcc
	global_load_dword v54, v[6:7], off
	v_add_co_u32_e32 v6, vcc, 0x3400, v6
	s_nop 0
	v_addc_co_u32_e32 v7, vcc, 0, v7, vcc
	global_load_dword v55, v[6:7], off
	v_add_co_u32_e32 v6, vcc, 0x3400, v6
	s_nop 0
	v_addc_co_u32_e32 v7, vcc, 0, v7, vcc
	global_load_dword v56, v[6:7], off
	v_add_co_u32_e32 v6, vcc, 0x3400, v6
	s_nop 0
	v_addc_co_u32_e32 v7, vcc, 0, v7, vcc
	global_load_dword v57, v[6:7], off
	v_add_co_u32_e32 v6, vcc, 0x3400, v6
	s_nop 0
	v_addc_co_u32_e32 v7, vcc, 0, v7, vcc
	global_load_dword v58, v[6:7], off
	v_add_co_u32_e32 v6, vcc, 0x3400, v6
	s_nop 0
	v_addc_co_u32_e32 v7, vcc, 0, v7, vcc
	global_load_dword v59, v[6:7], off
	v_add_co_u32_e32 v6, vcc, 0x3400, v6
	s_nop 0
	v_addc_co_u32_e32 v7, vcc, 0, v7, vcc
	global_load_dword v60, v[6:7], off
	v_add_co_u32_e32 v6, vcc, 0x3400, v6
	s_nop 0
	v_addc_co_u32_e32 v7, vcc, 0, v7, vcc
	global_load_dword v61, v[6:7], off
	v_add_co_u32_e32 v6, vcc, 0x3400, v6
	s_nop 0
	v_addc_co_u32_e32 v7, vcc, 0, v7, vcc
	global_load_dword v62, v[6:7], off
	v_add_co_u32_e32 v6, vcc, 0x3400, v6
	s_nop 0
	v_addc_co_u32_e32 v7, vcc, 0, v7, vcc
	global_load_dword v63, v[6:7], off
	v_add_co_u32_e32 v6, vcc, 0x3400, v6
	s_nop 0
	v_addc_co_u32_e32 v7, vcc, 0, v7, vcc
	global_load_dword v64, v[6:7], off
	v_add_co_u32_e32 v6, vcc, 0x3400, v6
	s_nop 0
	v_addc_co_u32_e32 v7, vcc, 0, v7, vcc
	global_load_dword v65, v[6:7], off
	v_add_co_u32_e32 v6, vcc, 0x3400, v6
	s_nop 0
	v_addc_co_u32_e32 v7, vcc, 0, v7, vcc
	global_load_dword v66, v[6:7], off
	v_add_co_u32_e32 v6, vcc, 0x3400, v6
	s_nop 0
	v_addc_co_u32_e32 v7, vcc, 0, v7, vcc
	global_load_dword v67, v[6:7], off
	v_add_co_u32_e32 v6, vcc, 0x3400, v6
	s_nop 0
	v_addc_co_u32_e32 v7, vcc, 0, v7, vcc
	global_load_dword v68, v[6:7], off
	v_add_co_u32_e32 v6, vcc, 0x3400, v6
	s_nop 0
	v_addc_co_u32_e32 v7, vcc, 0, v7, vcc
	global_load_dword v69, v[6:7], off
	v_add_co_u32_e32 v6, vcc, 0x3400, v6
	s_nop 0
	v_addc_co_u32_e32 v7, vcc, 0, v7, vcc
	global_load_dword v70, v[6:7], off
	v_add_co_u32_e32 v6, vcc, 0x3400, v6
	s_nop 0
	v_addc_co_u32_e32 v7, vcc, 0, v7, vcc
	global_load_dword v71, v[6:7], off
	v_add_co_u32_e32 v6, vcc, 0x3400, v6
	s_nop 0
	v_addc_co_u32_e32 v7, vcc, 0, v7, vcc
	global_load_dword v72, v[6:7], off
	v_add_co_u32_e32 v6, vcc, 0x3400, v6
	s_nop 0
	v_addc_co_u32_e32 v7, vcc, 0, v7, vcc
	global_load_dword v73, v[6:7], off
	v_add_co_u32_e32 v6, vcc, 0x3400, v6
	s_nop 0
	v_addc_co_u32_e32 v7, vcc, 0, v7, vcc
	global_load_dword v74, v[6:7], off
	v_add_co_u32_e32 v6, vcc, 0x3400, v6
	s_nop 0
	v_addc_co_u32_e32 v7, vcc, 0, v7, vcc
	global_load_dword v75, v[6:7], off
	v_add_co_u32_e32 v6, vcc, 0x3400, v6
	s_nop 0
	v_addc_co_u32_e32 v7, vcc, 0, v7, vcc
	global_load_dword v76, v[6:7], off
	v_add_co_u32_e32 v6, vcc, 0x3400, v6
	s_nop 0
	v_addc_co_u32_e32 v7, vcc, 0, v7, vcc
	global_load_dword v77, v[6:7], off
	v_add_co_u32_e32 v6, vcc, 0x3400, v6
	s_nop 0
	v_addc_co_u32_e32 v7, vcc, 0, v7, vcc
	global_load_dword v78, v[6:7], off
	v_add_co_u32_e32 v6, vcc, 0x3400, v6
	s_nop 0
	v_addc_co_u32_e32 v7, vcc, 0, v7, vcc
	global_load_dword v79, v[6:7], off
	v_add_co_u32_e32 v6, vcc, 0x3400, v6
	s_nop 0
	v_addc_co_u32_e32 v7, vcc, 0, v7, vcc
	global_load_dword v80, v[6:7], off
	v_add_co_u32_e32 v6, vcc, 0x3400, v6
	s_nop 0
	v_addc_co_u32_e32 v7, vcc, 0, v7, vcc
	global_load_dword v81, v[6:7], off
	v_add_co_u32_e32 v6, vcc, 0x3400, v6
	s_nop 0
	v_addc_co_u32_e32 v7, vcc, 0, v7, vcc
	global_load_dword v82, v[6:7], off
	v_add_co_u32_e32 v6, vcc, 0x3400, v6
	s_nop 0
	v_addc_co_u32_e32 v7, vcc, 0, v7, vcc
	global_load_dword v83, v[6:7], off
	v_add_co_u32_e32 v6, vcc, 0x3400, v6
	s_nop 0
	v_addc_co_u32_e32 v7, vcc, 0, v7, vcc
	global_load_dword v84, v[6:7], off
	v_add_co_u32_e32 v6, vcc, 0x3400, v6
	s_nop 0
	v_addc_co_u32_e32 v7, vcc, 0, v7, vcc
	global_load_dword v85, v[6:7], off
	v_add_co_u32_e32 v6, vcc, 0x3400, v6
	s_nop 0
	v_addc_co_u32_e32 v7, vcc, 0, v7, vcc
	global_load_dword v86, v[6:7], off
	v_add_co_u32_e32 v6, vcc, 0x3400, v6
	s_nop 0
	v_addc_co_u32_e32 v7, vcc, 0, v7, vcc
	global_load_dword v87, v[6:7], off
	v_add_co_u32_e32 v6, vcc, 0x3400, v6
	s_nop 0
	v_addc_co_u32_e32 v7, vcc, 0, v7, vcc
	global_load_dword v88, v[6:7], off
	v_add_co_u32_e32 v6, vcc, 0x3400, v6
	s_nop 0
	v_addc_co_u32_e32 v7, vcc, 0, v7, vcc
	global_load_dword v89, v[6:7], off
	v_add_co_u32_e32 v6, vcc, 0x3400, v6
	s_nop 0
	v_addc_co_u32_e32 v7, vcc, 0, v7, vcc
	global_load_dword v90, v[6:7], off
	v_add_co_u32_e32 v6, vcc, 0x3400, v6
	s_nop 0
	v_addc_co_u32_e32 v7, vcc, 0, v7, vcc
	global_load_dword v91, v[6:7], off
	v_add_co_u32_e32 v6, vcc, 0x3400, v6
	s_nop 0
	v_addc_co_u32_e32 v7, vcc, 0, v7, vcc
	global_load_dword v92, v[6:7], off
	v_add_co_u32_e32 v6, vcc, 0x3400, v6
	s_nop 0
	v_addc_co_u32_e32 v7, vcc, 0, v7, vcc
	global_load_dword v93, v[6:7], off
	v_add_co_u32_e32 v6, vcc, 0x3400, v6
	s_nop 0
	v_addc_co_u32_e32 v7, vcc, 0, v7, vcc
	global_load_dword v94, v[6:7], off
	v_add_co_u32_e32 v6, vcc, 0x3400, v6
	s_nop 0
	v_addc_co_u32_e32 v7, vcc, 0, v7, vcc
	s_waitcnt vmcnt(62)
	global_load_dword v95, v[6:7], off
	s_waitcnt vmcnt(62)
	v_cvt_pk_bf16_f32 v96, v32, v33
	s_waitcnt vmcnt(60)
	v_cvt_pk_bf16_f32 v97, v34, v35
	s_waitcnt vmcnt(58)
	v_cvt_pk_bf16_f32 v98, v36, v37
	s_waitcnt vmcnt(56)
	v_cvt_pk_bf16_f32 v99, v38, v39
	s_waitcnt vmcnt(54)
	v_cvt_pk_bf16_f32 v100, v40, v41
	s_waitcnt vmcnt(52)
	v_cvt_pk_bf16_f32 v101, v42, v43
	s_waitcnt vmcnt(50)
	v_cvt_pk_bf16_f32 v102, v44, v45
	s_waitcnt vmcnt(48)
	v_cvt_pk_bf16_f32 v103, v46, v47
	s_waitcnt vmcnt(46)
	v_cvt_pk_bf16_f32 v104, v48, v49
	s_waitcnt vmcnt(44)
	v_cvt_pk_bf16_f32 v105, v50, v51
	s_waitcnt vmcnt(42)
	v_cvt_pk_bf16_f32 v106, v52, v53
	s_waitcnt vmcnt(40)
	v_cvt_pk_bf16_f32 v107, v54, v55
	s_waitcnt vmcnt(38)
	v_cvt_pk_bf16_f32 v108, v56, v57
	s_waitcnt vmcnt(36)
	v_cvt_pk_bf16_f32 v109, v58, v59
	s_waitcnt vmcnt(34)
	v_cvt_pk_bf16_f32 v110, v60, v61
	s_waitcnt vmcnt(32)
	v_cvt_pk_bf16_f32 v111, v62, v63
	s_waitcnt vmcnt(30)
	v_cvt_pk_bf16_f32 v112, v64, v65
	s_waitcnt vmcnt(28)
	v_cvt_pk_bf16_f32 v113, v66, v67
	s_waitcnt vmcnt(26)
	v_cvt_pk_bf16_f32 v114, v68, v69
	s_waitcnt vmcnt(24)
	v_cvt_pk_bf16_f32 v115, v70, v71
	s_waitcnt vmcnt(22)
	v_cvt_pk_bf16_f32 v116, v72, v73
	s_waitcnt vmcnt(20)
	v_cvt_pk_bf16_f32 v117, v74, v75
	s_waitcnt vmcnt(18)
	v_cvt_pk_bf16_f32 v118, v76, v77
	s_waitcnt vmcnt(16)
	v_cvt_pk_bf16_f32 v119, v78, v79
	s_waitcnt vmcnt(14)
	v_cvt_pk_bf16_f32 v120, v80, v81
	s_waitcnt vmcnt(12)
	v_cvt_pk_bf16_f32 v121, v82, v83
	s_waitcnt vmcnt(10)
	v_cvt_pk_bf16_f32 v122, v84, v85
	s_waitcnt vmcnt(8)
	v_cvt_pk_bf16_f32 v123, v86, v87
	s_waitcnt vmcnt(6)
	v_cvt_pk_bf16_f32 v124, v88, v89
	s_waitcnt vmcnt(4)
	v_cvt_pk_bf16_f32 v125, v90, v91
	s_waitcnt vmcnt(2)
	v_cvt_pk_bf16_f32 v126, v92, v93
	s_waitcnt vmcnt(0)
	v_cvt_pk_bf16_f32 v127, v94, v95
	v_mov_b32_e32 v8, v4
	v_mov_b32_e32 v9, v5
	global_store_short v[8:9], v96, off
	global_store_short_d16_hi v[8:9], v96, off offset:512
	global_store_short v[8:9], v97, off offset:1024
	global_store_short_d16_hi v[8:9], v97, off offset:1536
	global_store_short v[8:9], v98, off offset:2048
	global_store_short_d16_hi v[8:9], v98, off offset:2560
	global_store_short v[8:9], v99, off offset:3072
	global_store_short_d16_hi v[8:9], v99, off offset:3584
	v_add_co_u32_e32 v8, vcc, 0x1000, v8
	s_nop 0
	v_addc_co_u32_e32 v9, vcc, 0, v9, vcc
	global_store_short v[8:9], v100, off
	global_store_short_d16_hi v[8:9], v100, off offset:512
	global_store_short v[8:9], v101, off offset:1024
	global_store_short_d16_hi v[8:9], v101, off offset:1536
	global_store_short v[8:9], v102, off offset:2048
	global_store_short_d16_hi v[8:9], v102, off offset:2560
	global_store_short v[8:9], v103, off offset:3072
	global_store_short_d16_hi v[8:9], v103, off offset:3584
	v_add_co_u32_e32 v8, vcc, 0x1000, v8
	s_nop 0
	v_addc_co_u32_e32 v9, vcc, 0, v9, vcc
	global_store_short v[8:9], v104, off
	global_store_short_d16_hi v[8:9], v104, off offset:512
	global_store_short v[8:9], v105, off offset:1024
	global_store_short_d16_hi v[8:9], v105, off offset:1536
	global_store_short v[8:9], v106, off offset:2048
	global_store_short_d16_hi v[8:9], v106, off offset:2560
	global_store_short v[8:9], v107, off offset:3072
	global_store_short_d16_hi v[8:9], v107, off offset:3584
	v_add_co_u32_e32 v8, vcc, 0x1000, v8
	s_nop 0
	v_addc_co_u32_e32 v9, vcc, 0, v9, vcc
	global_store_short v[8:9], v108, off
	global_store_short_d16_hi v[8:9], v108, off offset:512
	global_store_short v[8:9], v109, off offset:1024
	global_store_short_d16_hi v[8:9], v109, off offset:1536
	global_store_short v[8:9], v110, off offset:2048
	global_store_short_d16_hi v[8:9], v110, off offset:2560
	global_store_short v[8:9], v111, off offset:3072
	global_store_short_d16_hi v[8:9], v111, off offset:3584
	v_add_co_u32_e32 v8, vcc, 0x1000, v8
	s_nop 0
	v_addc_co_u32_e32 v9, vcc, 0, v9, vcc
	global_store_short v[8:9], v112, off
	global_store_short_d16_hi v[8:9], v112, off offset:512
	global_store_short v[8:9], v113, off offset:1024
	global_store_short_d16_hi v[8:9], v113, off offset:1536
	global_store_short v[8:9], v114, off offset:2048
	global_store_short_d16_hi v[8:9], v114, off offset:2560
	global_store_short v[8:9], v115, off offset:3072
	global_store_short_d16_hi v[8:9], v115, off offset:3584
	v_add_co_u32_e32 v8, vcc, 0x1000, v8
	s_nop 0
	v_addc_co_u32_e32 v9, vcc, 0, v9, vcc
	global_store_short v[8:9], v116, off
	global_store_short_d16_hi v[8:9], v116, off offset:512
	global_store_short v[8:9], v117, off offset:1024
	global_store_short_d16_hi v[8:9], v117, off offset:1536
	global_store_short v[8:9], v118, off offset:2048
	global_store_short_d16_hi v[8:9], v118, off offset:2560
	global_store_short v[8:9], v119, off offset:3072
	global_store_short_d16_hi v[8:9], v119, off offset:3584
	v_add_co_u32_e32 v8, vcc, 0x1000, v8
	s_nop 0
	v_addc_co_u32_e32 v9, vcc, 0, v9, vcc
	global_store_short v[8:9], v120, off
	global_store_short_d16_hi v[8:9], v120, off offset:512
	global_store_short v[8:9], v121, off offset:1024
	global_store_short_d16_hi v[8:9], v121, off offset:1536
	global_store_short v[8:9], v122, off offset:2048
	global_store_short_d16_hi v[8:9], v122, off offset:2560
	global_store_short v[8:9], v123, off offset:3072
	global_store_short_d16_hi v[8:9], v123, off offset:3584
	v_add_co_u32_e32 v8, vcc, 0x1000, v8
	s_nop 0
	v_addc_co_u32_e32 v9, vcc, 0, v9, vcc
	global_store_short v[8:9], v124, off
	global_store_short_d16_hi v[8:9], v124, off offset:512
	global_store_short v[8:9], v125, off offset:1024
	global_store_short_d16_hi v[8:9], v125, off offset:1536
	global_store_short v[8:9], v126, off offset:2048
	global_store_short_d16_hi v[8:9], v126, off offset:2560
	global_store_short v[8:9], v127, off offset:3072
	global_store_short_d16_hi v[8:9], v127, off offset:3584
	s_mov_b32 s8, 0
	s_movk_i32 s50, 0x3000
